# proj q/k-norm epilogue: xor16/xor32 reduction hops via v_permlane16/32_swap instead of ds_bpermute (bit-identical); on v91
# speedup vs baseline: 1.0090x; 1.0090x over previous
; #define PG8_GAS __attribute__((address_space(1)))
; __device__ __forceinline__ unsigned cvtpk(float lo, float hi) { f32x2 v = {lo, hi}; bf16x2_t b = __builtin_convertvector(v, bf16x2_t); return __builtin_bit_cast(unsigned, b); }
;     __device__ __forceinline__ void operator()(const f32x4 (&acc)[2][2][4][2], const Unit& u, int wr, int wc, int fr, int fq) const {
;     ...
;         if (u.pn < 4) {
;             const float* g = (u.pn < 2) ? gq : gk; const float sc = (u.pn < 2) ? 0.125f * 1.4426950408889634f : 1.0f;
;             f32x4 gv[2][2];
; #pragma unroll
;             for (int bj = 0; bj < 2; ++bj)
; #pragma unroll
;                 for (int n = 0; n < 2; ++n) gv[bj][n] = *(const PG8_GAS f32x4*)(g + 32 * bj + 8 * fq + 4 * n) * sc;
; #pragma unroll
;             for (int ai = 0; ai < 2; ++ai)
; #pragma unroll
;                 for (int m = 0; m < 4; ++m) {
;                     float ss = 0.f;
; #pragma unroll
;                     for (int bj = 0; bj < 2; ++bj)
; #pragma unroll
;                         for (int n = 0; n < 2; ++n) { const f32x4 x = acc[ai][bj][m][n]; ss += (x[0] * x[0] + x[1] * x[1]) + (x[2] * x[2] + x[3] * x[3]); }
;                     ss += __shfl_xor(ss, 16); ss += __shfl_xor(ss, 32);
;                     const float rstd = 1.0f / sqrtf(ss * (1.0f / 64.0f) + 1e-6f);
;                     bf16_t* p = O + (size_t)(row0 + ai * HALF + m * 16) * 3072 + colh;
; #pragma unroll
;                     for (int bj = 0; bj < 2; ++bj) {
;                         const f32x4 v0 = acc[ai][bj][m][0] * rstd * gv[bj][0], v1 = acc[ai][bj][m][1] * rstd * gv[bj][1];
;                         u32x4 w; w.x = cvtpk(v0[0], v0[1]); w.y = cvtpk(v0[2], v0[3]); w.z = cvtpk(v1[0], v1[1]); w.w = cvtpk(v1[2], v1[3]);
;                         __builtin_nontemporal_store(w, (PG8_GAS u32x4*)(p + 32 * bj));
.LBB0_259:
	s_andn2_b64 vcc, exec, s[6:7]
	s_cbranch_vccnz .LBB0_261
	s_cmp_lt_i32 s14, 2
	s_cselect_b64 vcc, -1, 0
	s_and_b64 s[6:7], vcc, exec
	s_cselect_b32 s7, s11, s65
	s_cselect_b32 s6, s10, s64
	global_load_dwordx4 v[152:155], v167, s[6:7] offset:16
	global_load_dwordx4 v[144:147], v167, s[6:7]
	v_cndmask_b32_e32 v170, 1.0, v225, vcc
	v_cmp_lt_i32_e32 vcc, v218, v213
	v_pk_mul_f32 v[178:179], v[130:131], v[130:131]
	s_waitcnt vmcnt(0)
	v_pk_mul_f32 v[148:149], v[170:171], v[146:147] op_sel_hi:[0,1]
	v_pk_mul_f32 v[150:151], v[170:171], v[144:145] op_sel_hi:[0,1]
	v_pk_mul_f32 v[144:145], v[170:171], v[154:155] op_sel_hi:[0,1]
	v_pk_mul_f32 v[146:147], v[170:171], v[152:153] op_sel_hi:[0,1]
	global_load_dwordx4 v[160:163], v167, s[6:7] offset:144
	global_load_dwordx4 v[152:155], v167, s[6:7] offset:128
	s_waitcnt vmcnt(0)
	v_pk_mul_f32 v[156:157], v[170:171], v[154:155] op_sel_hi:[0,1]
	v_pk_mul_f32 v[154:155], v[170:171], v[160:161] op_sel_hi:[0,1]
	v_cndmask_b32_e32 v160, v212, v218, vcc
	v_cmp_lt_i32_e32 vcc, v219, v213
	v_pk_mul_f32 v[158:159], v[170:171], v[152:153] op_sel_hi:[0,1]
	v_pk_mul_f32 v[152:153], v[170:171], v[162:163] op_sel_hi:[0,1]
	v_lshlrev_b32_e32 v171, 2, v160
	v_cndmask_b32_e32 v160, v212, v219, vcc
	v_lshlrev_b32_e32 v170, 2, v160
	v_pk_mul_f32 v[160:161], v[132:133], v[132:133]
	v_ashrrev_i32_e32 v163, 31, v0
	v_pk_mov_b32 v[180:181], v[178:179], v[160:161] op_sel:[1,0]
	v_mov_b32_e32 v179, v161
	v_pk_add_f32 v[160:161], v[180:181], v[178:179]
	v_pk_mul_f32 v[178:179], v[128:129], v[128:129]
	v_pk_mul_f32 v[180:181], v[126:127], v[126:127]
	v_mov_b32_e32 v162, v0
	v_pk_mov_b32 v[182:183], v[180:181], v[178:179] op_sel:[1,0]
	v_mov_b32_e32 v181, v179
	v_pk_add_f32 v[178:179], v[182:183], v[180:181]
	v_mul_f32_e32 v0, v118, v118
	v_mul_f32_e32 v180, v119, v119
	v_pk_add_f32 v[160:161], v[160:161], v[160:161] op_sel:[0,1] op_sel_hi:[1,0]
	v_pk_add_f32 v[178:179], v[178:179], v[178:179] op_sel:[0,1] op_sel_hi:[1,0]
	v_mov_b32_e32 v161, v0
	v_mov_b32_e32 v179, v180
	v_mul_f32_e32 v0, v123, v123
	v_mul_f32_e32 v181, v120, v120
	v_pk_add_f32 v[160:161], v[160:161], v[178:179]
	v_pk_fma_f32 v[178:179], v[122:123], v[122:123], v[0:1] op_sel_hi:[1,1,0]
	v_mul_f32_e32 v0, v125, v125
	v_mul_f32_e32 v182, v121, v121
	v_mov_b32_e32 v179, v181
	v_pk_fma_f32 v[180:181], v[124:125], v[124:125], v[0:1] op_sel_hi:[1,1,0]
	v_lshlrev_b64 v[162:163], 1, v[162:163]
	v_mov_b32_e32 v181, v182
	v_pk_add_f32 v[178:179], v[178:179], v[180:181]
	s_nop 0
	v_pk_add_f32 v[160:161], v[160:161], v[178:179]
	s_nop 0
	v_add_f32_e32 v0, v160, v161
	s_waitcnt lgkmcnt(0)
	v_mov_b32_e32 v160, v0
	v_mov_b32_e32 v253, v0
	s_nop 1
	v_permlane16_swap_b32_e32 v160, v253
	v_add_f32_e32 v0, v160, v253
	s_waitcnt lgkmcnt(0)
	v_mov_b32_e32 v160, v0
	v_mov_b32_e32 v253, v0
	s_nop 1
	v_permlane32_swap_b32_e32 v160, v253
	v_add_f32_e32 v0, v160, v253
	v_fmamk_f32 v0, v0, 0x3c800000, v220
	v_cmp_gt_f32_e32 vcc, s45, v0
	v_mul_f32_e32 v160, 0x4f800000, v0
	s_nop 0
	v_cndmask_b32_e32 v0, v0, v160, vcc
	v_sqrt_f32_e32 v160, v0
	s_nop 0
	v_add_u32_e32 v161, -1, v160
	v_fma_f32 v178, -v161, v160, v0
	v_cmp_ge_f32_e64 s[6:7], 0, v178
	v_add_u32_e32 v178, 1, v160
	s_nop 0
	v_cndmask_b32_e64 v161, v160, v161, s[6:7]
	v_fma_f32 v160, -v178, v160, v0
	v_cmp_lt_f32_e64 s[6:7], 0, v160
	s_nop 1
	v_cndmask_b32_e64 v160, v161, v178, s[6:7]
	v_mul_f32_e32 v161, 0x37800000, v160
	v_cndmask_b32_e32 v160, v160, v161, vcc
	v_cmp_class_f32_e32 vcc, v0, v221
	s_nop 1
	v_cndmask_b32_e32 v0, v160, v0, vcc
	v_div_scale_f32 v160, s[6:7], v0, v0, 1.0
	v_rcp_f32_e32 v161, v160
	s_nop 0
	v_fma_f32 v178, -v160, v161, 1.0
	v_fmac_f32_e32 v161, v178, v161
	v_div_scale_f32 v178, vcc, 1.0, v0, 1.0
	v_mul_f32_e32 v179, v178, v161
	v_fma_f32 v180, -v160, v179, v178
	v_fmac_f32_e32 v179, v180, v161
	v_fma_f32 v160, -v160, v179, v178
	v_div_fmas_f32 v160, v160, v161, v179
	v_div_fixup_f32 v0, v160, v0, 1.0
	v_mov_b64_e32 v[160:161], s[8:9]
	v_pk_mul_f32 v[130:131], v[130:131], v[0:1] op_sel_hi:[1,0]
	v_pk_mul_f32 v[132:133], v[132:133], v[0:1] op_sel_hi:[1,0]
	v_pk_mul_f32 v[126:127], v[126:127], v[0:1] op_sel_hi:[1,0]
	v_pk_mul_f32 v[128:129], v[128:129], v[0:1] op_sel_hi:[1,0]
	v_mad_i64_i32 v[178:179], s[6:7], v177, s44, v[160:161]
	v_pk_mul_f32 v[132:133], v[148:149], v[132:133]
	v_pk_mul_f32 v[130:131], v[150:151], v[130:131]
	v_pk_mul_f32 v[180:181], v[144:145], v[128:129]
	v_pk_mul_f32 v[128:129], v[146:147], v[126:127]
	v_lshl_add_u64 v[178:179], v[178:179], 0, v[162:163]
	v_cvt_pk_bf16_f32 v126, v130, v131
	v_cvt_pk_bf16_f32 v127, v132, v133
	v_cvt_pk_bf16_f32 v128, v128, v129
	v_cvt_pk_bf16_f32 v129, v180, v181
	v_pk_mul_f32 v[122:123], v[122:123], v[0:1] op_sel_hi:[1,0]
	v_pk_mul_f32 v[124:125], v[124:125], v[0:1] op_sel_hi:[1,0]
	v_pk_mul_f32 v[118:119], v[118:119], v[0:1] op_sel_hi:[1,0]
	v_pk_mul_f32 v[120:121], v[120:121], v[0:1] op_sel_hi:[1,0]
	global_store_dwordx4 v[178:179], v[126:129], off nt
	v_pk_mul_f32 v[124:125], v[156:157], v[124:125]
	v_pk_mul_f32 v[122:123], v[158:159], v[122:123]
	v_pk_mul_f32 v[126:127], v[152:153], v[120:121]
	v_pk_mul_f32 v[120:121], v[154:155], v[118:119]
	v_cvt_pk_bf16_f32 v118, v122, v123
	v_cvt_pk_bf16_f32 v119, v124, v125
	v_cvt_pk_bf16_f32 v120, v120, v121
	v_cvt_pk_bf16_f32 v121, v126, v127
	global_store_dwordx4 v[178:179], v[118:121], off offset:64 nt
	v_mul_f32_e32 v0, v102, v102
	s_nop 0
	v_pk_mul_f32 v[118:119], v[116:117], v[116:117]
	v_pk_mul_f32 v[120:121], v[114:115], v[114:115]
	s_nop 0
	v_pk_mov_b32 v[122:123], v[120:121], v[118:119] op_sel:[1,0]
	v_mov_b32_e32 v121, v119
	v_pk_add_f32 v[118:119], v[122:123], v[120:121]
	v_pk_mul_f32 v[120:121], v[112:113], v[112:113]
	v_pk_mul_f32 v[122:123], v[110:111], v[110:111]
	v_pk_add_f32 v[118:119], v[118:119], v[118:119] op_sel:[0,1] op_sel_hi:[1,0]
	v_pk_mov_b32 v[124:125], v[122:123], v[120:121] op_sel:[1,0]
	v_mov_b32_e32 v123, v121
	v_pk_add_f32 v[120:121], v[124:125], v[122:123]
	v_mul_f32_e32 v122, v103, v103
	v_pk_add_f32 v[120:121], v[120:121], v[120:121] op_sel:[0,1] op_sel_hi:[1,0]
	v_mov_b32_e32 v119, v0
	v_mov_b32_e32 v121, v122
	v_mul_f32_e32 v0, v107, v107
	v_mul_f32_e32 v123, v104, v104
	v_pk_add_f32 v[118:119], v[118:119], v[120:121]
	v_pk_fma_f32 v[120:121], v[106:107], v[106:107], v[0:1] op_sel_hi:[1,1,0]
	v_mul_f32_e32 v0, v109, v109
	v_mul_f32_e32 v124, v105, v105
	v_mov_b32_e32 v121, v123
	v_pk_fma_f32 v[122:123], v[108:109], v[108:109], v[0:1] op_sel_hi:[1,1,0]
	s_nop 0
	v_mov_b32_e32 v123, v124
	v_pk_add_f32 v[120:121], v[120:121], v[122:123]
	s_nop 0
	v_pk_add_f32 v[118:119], v[118:119], v[120:121]
	s_nop 0
	v_add_f32_e32 v0, v118, v119
	s_waitcnt lgkmcnt(0)
; #define PG8_GAS __attribute__((address_space(1)))
; __device__ __forceinline__ unsigned cvtpk(float lo, float hi) { f32x2 v = {lo, hi}; bf16x2_t b = __builtin_convertvector(v, bf16x2_t); return __builtin_bit_cast(unsigned, b); }
;     __device__ __forceinline__ void operator()(const f32x4 (&acc)[2][2][4][2], const Unit& u, int wr, int wc, int fr, int fq) const {
;     ...
;                     float ss = 0.f;
; #pragma unroll
;                     for (int bj = 0; bj < 2; ++bj)
; #pragma unroll
;                         for (int n = 0; n < 2; ++n) { const f32x4 x = acc[ai][bj][m][n]; ss += (x[0] * x[0] + x[1] * x[1]) + (x[2] * x[2] + x[3] * x[3]); }
;                     ss += __shfl_xor(ss, 16); ss += __shfl_xor(ss, 32);
;                     const float rstd = 1.0f / sqrtf(ss * (1.0f / 64.0f) + 1e-6f);
;                     bf16_t* p = O + (size_t)(row0 + ai * HALF + m * 16) * 3072 + colh;
; #pragma unroll
;                     for (int bj = 0; bj < 2; ++bj) {
;                         const f32x4 v0 = acc[ai][bj][m][0] * rstd * gv[bj][0], v1 = acc[ai][bj][m][1] * rstd * gv[bj][1];
;                         u32x4 w; w.x = cvtpk(v0[0], v0[1]); w.y = cvtpk(v0[2], v0[3]); w.z = cvtpk(v1[0], v1[1]); w.w = cvtpk(v1[2], v1[3]);
;                         __builtin_nontemporal_store(w, (PG8_GAS u32x4*)(p + 32 * bj));
;                     }
	v_mov_b32_e32 v118, v0
	v_mov_b32_e32 v253, v0
	s_nop 1
	v_permlane16_swap_b32_e32 v118, v253
	v_add_f32_e32 v0, v118, v253
	s_waitcnt lgkmcnt(0)
	v_mov_b32_e32 v118, v0
	v_mov_b32_e32 v253, v0
	s_nop 1
	v_permlane32_swap_b32_e32 v118, v253
	v_add_f32_e32 v0, v118, v253
	v_fmamk_f32 v0, v0, 0x3c800000, v220
	v_cmp_gt_f32_e32 vcc, s45, v0
	v_mul_f32_e32 v118, 0x4f800000, v0
	s_nop 0
	v_cndmask_b32_e32 v0, v0, v118, vcc
	v_sqrt_f32_e32 v118, v0
	s_nop 0
	v_add_u32_e32 v119, -1, v118
	v_fma_f32 v120, -v119, v118, v0
	v_cmp_ge_f32_e64 s[6:7], 0, v120
	v_add_u32_e32 v120, 1, v118
	s_nop 0
	v_cndmask_b32_e64 v119, v118, v119, s[6:7]
	v_fma_f32 v118, -v120, v118, v0
	v_cmp_lt_f32_e64 s[6:7], 0, v118
	s_nop 1
	v_cndmask_b32_e64 v118, v119, v120, s[6:7]
	v_mul_f32_e32 v119, 0x37800000, v118
	v_cndmask_b32_e32 v118, v118, v119, vcc
	v_cmp_class_f32_e32 vcc, v0, v221
	s_nop 1
	v_cndmask_b32_e32 v0, v118, v0, vcc
	v_div_scale_f32 v118, s[6:7], v0, v0, 1.0
	v_rcp_f32_e32 v119, v118
	s_nop 0
	v_fma_f32 v120, -v118, v119, 1.0
	v_fmac_f32_e32 v119, v120, v119
	v_div_scale_f32 v120, vcc, 1.0, v0, 1.0
	v_mul_f32_e32 v121, v120, v119
	v_fma_f32 v122, -v118, v121, v120
	v_fmac_f32_e32 v121, v122, v119
	v_fma_f32 v118, -v118, v121, v120
	v_div_fmas_f32 v118, v118, v119, v121
	v_div_fixup_f32 v0, v118, v0, 1.0
	v_pk_mul_f32 v[114:115], v[114:115], v[0:1] op_sel_hi:[1,0]
	v_pk_mul_f32 v[116:117], v[116:117], v[0:1] op_sel_hi:[1,0]
	v_pk_mul_f32 v[110:111], v[110:111], v[0:1] op_sel_hi:[1,0]
	v_pk_mul_f32 v[112:113], v[112:113], v[0:1] op_sel_hi:[1,0]
	v_mad_i64_i32 v[118:119], s[6:7], v176, s44, v[160:161]
	v_pk_mul_f32 v[116:117], v[148:149], v[116:117]
	v_pk_mul_f32 v[114:115], v[150:151], v[114:115]
	v_pk_mul_f32 v[120:121], v[144:145], v[112:113]
	v_pk_mul_f32 v[112:113], v[146:147], v[110:111]
	v_lshl_add_u64 v[118:119], v[118:119], 0, v[162:163]
	v_cvt_pk_bf16_f32 v110, v114, v115
	v_cvt_pk_bf16_f32 v111, v116, v117
	v_cvt_pk_bf16_f32 v112, v112, v113
	v_cvt_pk_bf16_f32 v113, v120, v121
	v_pk_mul_f32 v[106:107], v[106:107], v[0:1] op_sel_hi:[1,0]
	v_pk_mul_f32 v[108:109], v[108:109], v[0:1] op_sel_hi:[1,0]
	v_pk_mul_f32 v[102:103], v[102:103], v[0:1] op_sel_hi:[1,0]
	v_pk_mul_f32 v[104:105], v[104:105], v[0:1] op_sel_hi:[1,0]
	global_store_dwordx4 v[118:119], v[110:113], off nt
	v_pk_mul_f32 v[108:109], v[156:157], v[108:109]
	v_pk_mul_f32 v[106:107], v[158:159], v[106:107]
	v_pk_mul_f32 v[110:111], v[152:153], v[104:105]
	v_pk_mul_f32 v[104:105], v[154:155], v[102:103]
	v_cvt_pk_bf16_f32 v102, v106, v107
	v_cvt_pk_bf16_f32 v103, v108, v109
	v_cvt_pk_bf16_f32 v104, v104, v105
	v_cvt_pk_bf16_f32 v105, v110, v111
	global_store_dwordx4 v[118:119], v[102:105], off offset:64 nt
	v_mul_f32_e32 v0, v86, v86
	s_nop 0
	v_pk_mul_f32 v[102:103], v[100:101], v[100:101]
	v_pk_mul_f32 v[104:105], v[98:99], v[98:99]
	s_nop 0
	v_pk_mov_b32 v[106:107], v[104:105], v[102:103] op_sel:[1,0]
	v_mov_b32_e32 v105, v103
	v_pk_add_f32 v[102:103], v[106:107], v[104:105]
	v_pk_mul_f32 v[104:105], v[96:97], v[96:97]
	v_pk_mul_f32 v[106:107], v[94:95], v[94:95]
	v_pk_add_f32 v[102:103], v[102:103], v[102:103] op_sel:[0,1] op_sel_hi:[1,0]
	v_pk_mov_b32 v[108:109], v[106:107], v[104:105] op_sel:[1,0]
	v_mov_b32_e32 v107, v105
	v_pk_add_f32 v[104:105], v[108:109], v[106:107]
	v_mul_f32_e32 v106, v87, v87
	v_pk_add_f32 v[104:105], v[104:105], v[104:105] op_sel:[0,1] op_sel_hi:[1,0]
	v_mov_b32_e32 v103, v0
	v_mov_b32_e32 v105, v106
	v_mul_f32_e32 v0, v91, v91
	v_mul_f32_e32 v107, v88, v88
	v_pk_add_f32 v[102:103], v[102:103], v[104:105]
	v_pk_fma_f32 v[104:105], v[90:91], v[90:91], v[0:1] op_sel_hi:[1,1,0]
	v_mul_f32_e32 v0, v93, v93
	v_mul_f32_e32 v108, v89, v89
	v_mov_b32_e32 v105, v107
	v_pk_fma_f32 v[106:107], v[92:93], v[92:93], v[0:1] op_sel_hi:[1,1,0]
	s_nop 0
	v_mov_b32_e32 v107, v108
	v_pk_add_f32 v[104:105], v[104:105], v[106:107]
	s_nop 0
	v_pk_add_f32 v[102:103], v[102:103], v[104:105]
	s_nop 0
	v_add_f32_e32 v0, v102, v103
	s_waitcnt lgkmcnt(0)
	v_mov_b32_e32 v102, v0
	v_mov_b32_e32 v253, v0
	s_nop 1
	v_permlane16_swap_b32_e32 v102, v253
	v_add_f32_e32 v0, v102, v253
	s_waitcnt lgkmcnt(0)
	v_mov_b32_e32 v102, v0
	v_mov_b32_e32 v253, v0
	s_nop 1
	v_permlane32_swap_b32_e32 v102, v253
	v_add_f32_e32 v0, v102, v253
	v_fmamk_f32 v0, v0, 0x3c800000, v220
	v_cmp_gt_f32_e32 vcc, s45, v0
	v_mul_f32_e32 v102, 0x4f800000, v0
	s_nop 0
	v_cndmask_b32_e32 v0, v0, v102, vcc
	v_sqrt_f32_e32 v102, v0
	s_nop 0
	v_add_u32_e32 v103, -1, v102
	v_fma_f32 v104, -v103, v102, v0
	v_cmp_ge_f32_e64 s[6:7], 0, v104
	v_add_u32_e32 v104, 1, v102
	s_nop 0
	v_cndmask_b32_e64 v103, v102, v103, s[6:7]
	v_fma_f32 v102, -v104, v102, v0
	v_cmp_lt_f32_e64 s[6:7], 0, v102
	s_nop 1
	v_cndmask_b32_e64 v102, v103, v104, s[6:7]
	v_mul_f32_e32 v103, 0x37800000, v102
	v_cndmask_b32_e32 v102, v102, v103, vcc
	v_cmp_class_f32_e32 vcc, v0, v221
	s_nop 1
	v_cndmask_b32_e32 v0, v102, v0, vcc
	v_div_scale_f32 v102, s[6:7], v0, v0, 1.0
	v_rcp_f32_e32 v103, v102
	s_nop 0
	v_fma_f32 v104, -v102, v103, 1.0
	v_fmac_f32_e32 v103, v104, v103
	v_div_scale_f32 v104, vcc, 1.0, v0, 1.0
	v_mul_f32_e32 v105, v104, v103
	v_fma_f32 v106, -v102, v105, v104
	v_fmac_f32_e32 v105, v106, v103
	v_fma_f32 v102, -v102, v105, v104
	v_div_fmas_f32 v102, v102, v103, v105
	v_div_fixup_f32 v0, v102, v0, 1.0
	v_pk_mul_f32 v[98:99], v[98:99], v[0:1] op_sel_hi:[1,0]
	v_pk_mul_f32 v[100:101], v[100:101], v[0:1] op_sel_hi:[1,0]
	v_pk_mul_f32 v[94:95], v[94:95], v[0:1] op_sel_hi:[1,0]
	v_pk_mul_f32 v[96:97], v[96:97], v[0:1] op_sel_hi:[1,0]
	v_mad_i64_i32 v[102:103], s[6:7], v175, s44, v[160:161]
	v_pk_mul_f32 v[100:101], v[148:149], v[100:101]
; #define PG8_GAS __attribute__((address_space(1)))
; __device__ __forceinline__ unsigned cvtpk(float lo, float hi) { f32x2 v = {lo, hi}; bf16x2_t b = __builtin_convertvector(v, bf16x2_t); return __builtin_bit_cast(unsigned, b); }
;     __device__ __forceinline__ void operator()(const f32x4 (&acc)[2][2][4][2], const Unit& u, int wr, int wc, int fr, int fq) const {
;     ...
;                     float ss = 0.f;
; #pragma unroll
;                     for (int bj = 0; bj < 2; ++bj)
; #pragma unroll
;                         for (int n = 0; n < 2; ++n) { const f32x4 x = acc[ai][bj][m][n]; ss += (x[0] * x[0] + x[1] * x[1]) + (x[2] * x[2] + x[3] * x[3]); }
;                     ss += __shfl_xor(ss, 16); ss += __shfl_xor(ss, 32);
;                     const float rstd = 1.0f / sqrtf(ss * (1.0f / 64.0f) + 1e-6f);
;                     bf16_t* p = O + (size_t)(row0 + ai * HALF + m * 16) * 3072 + colh;
; #pragma unroll
;                     for (int bj = 0; bj < 2; ++bj) {
;                         const f32x4 v0 = acc[ai][bj][m][0] * rstd * gv[bj][0], v1 = acc[ai][bj][m][1] * rstd * gv[bj][1];
;                         u32x4 w; w.x = cvtpk(v0[0], v0[1]); w.y = cvtpk(v0[2], v0[3]); w.z = cvtpk(v1[0], v1[1]); w.w = cvtpk(v1[2], v1[3]);
;                         __builtin_nontemporal_store(w, (PG8_GAS u32x4*)(p + 32 * bj));
;                     }
	v_pk_mul_f32 v[98:99], v[150:151], v[98:99]
	v_pk_mul_f32 v[104:105], v[144:145], v[96:97]
	v_pk_mul_f32 v[96:97], v[146:147], v[94:95]
	v_lshl_add_u64 v[102:103], v[102:103], 0, v[162:163]
	v_cvt_pk_bf16_f32 v94, v98, v99
	v_cvt_pk_bf16_f32 v95, v100, v101
	v_cvt_pk_bf16_f32 v96, v96, v97
	v_cvt_pk_bf16_f32 v97, v104, v105
	v_pk_mul_f32 v[90:91], v[90:91], v[0:1] op_sel_hi:[1,0]
	v_pk_mul_f32 v[92:93], v[92:93], v[0:1] op_sel_hi:[1,0]
	v_pk_mul_f32 v[86:87], v[86:87], v[0:1] op_sel_hi:[1,0]
	v_pk_mul_f32 v[88:89], v[88:89], v[0:1] op_sel_hi:[1,0]
	global_store_dwordx4 v[102:103], v[94:97], off nt
	v_pk_mul_f32 v[92:93], v[156:157], v[92:93]
	v_pk_mul_f32 v[90:91], v[158:159], v[90:91]
	v_pk_mul_f32 v[94:95], v[152:153], v[88:89]
	v_pk_mul_f32 v[88:89], v[154:155], v[86:87]
	v_cvt_pk_bf16_f32 v86, v90, v91
	v_cvt_pk_bf16_f32 v87, v92, v93
	v_cvt_pk_bf16_f32 v88, v88, v89
	v_cvt_pk_bf16_f32 v89, v94, v95
	global_store_dwordx4 v[102:103], v[86:89], off offset:64 nt
	v_mul_f32_e32 v0, v70, v70
	s_nop 0
	v_pk_mul_f32 v[86:87], v[84:85], v[84:85]
	v_pk_mul_f32 v[88:89], v[82:83], v[82:83]
	s_nop 0
	v_pk_mov_b32 v[90:91], v[88:89], v[86:87] op_sel:[1,0]
	v_mov_b32_e32 v89, v87
	v_pk_add_f32 v[86:87], v[90:91], v[88:89]
	v_pk_mul_f32 v[88:89], v[80:81], v[80:81]
	v_pk_mul_f32 v[90:91], v[78:79], v[78:79]
	v_pk_add_f32 v[86:87], v[86:87], v[86:87] op_sel:[0,1] op_sel_hi:[1,0]
	v_pk_mov_b32 v[92:93], v[90:91], v[88:89] op_sel:[1,0]
	v_mov_b32_e32 v91, v89
	v_pk_add_f32 v[88:89], v[92:93], v[90:91]
	v_mul_f32_e32 v90, v71, v71
	v_pk_add_f32 v[88:89], v[88:89], v[88:89] op_sel:[0,1] op_sel_hi:[1,0]
	v_mov_b32_e32 v87, v0
	v_mov_b32_e32 v89, v90
	v_mul_f32_e32 v0, v75, v75
	v_mul_f32_e32 v91, v72, v72
	v_pk_add_f32 v[86:87], v[86:87], v[88:89]
	v_pk_fma_f32 v[88:89], v[74:75], v[74:75], v[0:1] op_sel_hi:[1,1,0]
	v_mul_f32_e32 v0, v77, v77
	v_mul_f32_e32 v92, v73, v73
	v_mov_b32_e32 v89, v91
	v_pk_fma_f32 v[90:91], v[76:77], v[76:77], v[0:1] op_sel_hi:[1,1,0]
	s_nop 0
	v_mov_b32_e32 v91, v92
	v_pk_add_f32 v[88:89], v[88:89], v[90:91]
	s_nop 0
	v_pk_add_f32 v[86:87], v[86:87], v[88:89]
	s_nop 0
	v_add_f32_e32 v0, v86, v87
	s_waitcnt lgkmcnt(0)
	v_mov_b32_e32 v86, v0
	v_mov_b32_e32 v253, v0
	s_nop 1
	v_permlane16_swap_b32_e32 v86, v253
	v_add_f32_e32 v0, v86, v253
	s_waitcnt lgkmcnt(0)
	v_mov_b32_e32 v86, v0
	v_mov_b32_e32 v253, v0
	s_nop 1
	v_permlane32_swap_b32_e32 v86, v253
	v_add_f32_e32 v0, v86, v253
	v_fmamk_f32 v0, v0, 0x3c800000, v220
	v_cmp_gt_f32_e32 vcc, s45, v0
	v_mul_f32_e32 v86, 0x4f800000, v0
	s_nop 0
	v_cndmask_b32_e32 v0, v0, v86, vcc
	v_sqrt_f32_e32 v86, v0
	s_nop 0
	v_add_u32_e32 v87, -1, v86
	v_fma_f32 v88, -v87, v86, v0
	v_cmp_ge_f32_e64 s[6:7], 0, v88
	v_add_u32_e32 v88, 1, v86
	s_nop 0
	v_cndmask_b32_e64 v87, v86, v87, s[6:7]
	v_fma_f32 v86, -v88, v86, v0
	v_cmp_lt_f32_e64 s[6:7], 0, v86
	s_nop 1
	v_cndmask_b32_e64 v86, v87, v88, s[6:7]
	v_mul_f32_e32 v87, 0x37800000, v86
	v_cndmask_b32_e32 v86, v86, v87, vcc
	v_cmp_class_f32_e32 vcc, v0, v221
	s_nop 1
	v_cndmask_b32_e32 v0, v86, v0, vcc
	v_div_scale_f32 v86, s[6:7], v0, v0, 1.0
	v_rcp_f32_e32 v87, v86
	s_nop 0
	v_fma_f32 v88, -v86, v87, 1.0
	v_fmac_f32_e32 v87, v88, v87
	v_div_scale_f32 v88, vcc, 1.0, v0, 1.0
	v_mul_f32_e32 v89, v88, v87
	v_fma_f32 v90, -v86, v89, v88
	v_fmac_f32_e32 v89, v90, v87
	v_fma_f32 v86, -v86, v89, v88
	v_div_fmas_f32 v86, v86, v87, v89
	v_div_fixup_f32 v0, v86, v0, 1.0
	v_pk_mul_f32 v[82:83], v[82:83], v[0:1] op_sel_hi:[1,0]
	v_pk_mul_f32 v[84:85], v[84:85], v[0:1] op_sel_hi:[1,0]
	v_pk_mul_f32 v[78:79], v[78:79], v[0:1] op_sel_hi:[1,0]
	v_pk_mul_f32 v[80:81], v[80:81], v[0:1] op_sel_hi:[1,0]
	v_mad_i64_i32 v[86:87], s[6:7], v174, s44, v[160:161]
	v_pk_mul_f32 v[84:85], v[148:149], v[84:85]
	v_pk_mul_f32 v[82:83], v[150:151], v[82:83]
	v_pk_mul_f32 v[88:89], v[144:145], v[80:81]
	v_pk_mul_f32 v[80:81], v[146:147], v[78:79]
	v_lshl_add_u64 v[86:87], v[86:87], 0, v[162:163]
	v_cvt_pk_bf16_f32 v78, v82, v83
	v_cvt_pk_bf16_f32 v79, v84, v85
	v_cvt_pk_bf16_f32 v80, v80, v81
	v_cvt_pk_bf16_f32 v81, v88, v89
	v_pk_mul_f32 v[74:75], v[74:75], v[0:1] op_sel_hi:[1,0]
	v_pk_mul_f32 v[76:77], v[76:77], v[0:1] op_sel_hi:[1,0]
	v_pk_mul_f32 v[70:71], v[70:71], v[0:1] op_sel_hi:[1,0]
	v_pk_mul_f32 v[72:73], v[72:73], v[0:1] op_sel_hi:[1,0]
	global_store_dwordx4 v[86:87], v[78:81], off nt
	v_pk_mul_f32 v[76:77], v[156:157], v[76:77]
	v_pk_mul_f32 v[74:75], v[158:159], v[74:75]
	v_pk_mul_f32 v[78:79], v[152:153], v[72:73]
	v_pk_mul_f32 v[72:73], v[154:155], v[70:71]
	v_cvt_pk_bf16_f32 v70, v74, v75
	v_cvt_pk_bf16_f32 v71, v76, v77
	v_cvt_pk_bf16_f32 v72, v72, v73
	v_cvt_pk_bf16_f32 v73, v78, v79
	global_store_dwordx4 v[86:87], v[70:73], off offset:64 nt
	v_mul_f32_e32 v0, v54, v54
	s_nop 0
	v_pk_mul_f32 v[70:71], v[68:69], v[68:69]
	v_pk_mul_f32 v[72:73], v[66:67], v[66:67]
	s_nop 0
	v_pk_mov_b32 v[74:75], v[72:73], v[70:71] op_sel:[1,0]
	v_mov_b32_e32 v73, v71
	v_pk_add_f32 v[70:71], v[74:75], v[72:73]
	v_pk_mul_f32 v[72:73], v[64:65], v[64:65]
	v_pk_mul_f32 v[74:75], v[62:63], v[62:63]
	v_pk_add_f32 v[70:71], v[70:71], v[70:71] op_sel:[0,1] op_sel_hi:[1,0]
	v_pk_mov_b32 v[76:77], v[74:75], v[72:73] op_sel:[1,0]
	v_mov_b32_e32 v75, v73
	v_pk_add_f32 v[72:73], v[76:77], v[74:75]
	v_mul_f32_e32 v74, v55, v55
	v_pk_add_f32 v[72:73], v[72:73], v[72:73] op_sel:[0,1] op_sel_hi:[1,0]
	v_mov_b32_e32 v71, v0
	v_mov_b32_e32 v73, v74
	v_mul_f32_e32 v0, v59, v59
	v_mul_f32_e32 v75, v56, v56
	v_pk_add_f32 v[70:71], v[70:71], v[72:73]
	v_pk_fma_f32 v[72:73], v[58:59], v[58:59], v[0:1] op_sel_hi:[1,1,0]
	v_mul_f32_e32 v0, v61, v61
	v_mul_f32_e32 v76, v57, v57
	v_mov_b32_e32 v73, v75
	v_pk_fma_f32 v[74:75], v[60:61], v[60:61], v[0:1] op_sel_hi:[1,1,0]
	s_nop 0
	v_mov_b32_e32 v75, v76
	v_pk_add_f32 v[72:73], v[72:73], v[74:75]
	s_nop 0
	v_pk_add_f32 v[70:71], v[70:71], v[72:73]
	s_nop 0
	v_add_f32_e32 v0, v70, v71
	s_waitcnt lgkmcnt(0)
; #define PG8_GAS __attribute__((address_space(1)))
; __device__ __forceinline__ unsigned cvtpk(float lo, float hi) { f32x2 v = {lo, hi}; bf16x2_t b = __builtin_convertvector(v, bf16x2_t); return __builtin_bit_cast(unsigned, b); }
;     __device__ __forceinline__ void operator()(const f32x4 (&acc)[2][2][4][2], const Unit& u, int wr, int wc, int fr, int fq) const {
;     ...
;                     float ss = 0.f;
; #pragma unroll
;                     for (int bj = 0; bj < 2; ++bj)
; #pragma unroll
;                         for (int n = 0; n < 2; ++n) { const f32x4 x = acc[ai][bj][m][n]; ss += (x[0] * x[0] + x[1] * x[1]) + (x[2] * x[2] + x[3] * x[3]); }
;                     ss += __shfl_xor(ss, 16); ss += __shfl_xor(ss, 32);
;                     const float rstd = 1.0f / sqrtf(ss * (1.0f / 64.0f) + 1e-6f);
;                     bf16_t* p = O + (size_t)(row0 + ai * HALF + m * 16) * 3072 + colh;
; #pragma unroll
;                     for (int bj = 0; bj < 2; ++bj) {
;                         const f32x4 v0 = acc[ai][bj][m][0] * rstd * gv[bj][0], v1 = acc[ai][bj][m][1] * rstd * gv[bj][1];
;                         u32x4 w; w.x = cvtpk(v0[0], v0[1]); w.y = cvtpk(v0[2], v0[3]); w.z = cvtpk(v1[0], v1[1]); w.w = cvtpk(v1[2], v1[3]);
;                         __builtin_nontemporal_store(w, (PG8_GAS u32x4*)(p + 32 * bj));
;                     }
	v_mov_b32_e32 v70, v0
	v_mov_b32_e32 v253, v0
	s_nop 1
	v_permlane16_swap_b32_e32 v70, v253
	v_add_f32_e32 v0, v70, v253
	s_waitcnt lgkmcnt(0)
	v_mov_b32_e32 v70, v0
	v_mov_b32_e32 v253, v0
	s_nop 1
	v_permlane32_swap_b32_e32 v70, v253
	v_add_f32_e32 v0, v70, v253
	v_fmamk_f32 v0, v0, 0x3c800000, v220
	v_cmp_gt_f32_e32 vcc, s45, v0
	v_mul_f32_e32 v70, 0x4f800000, v0
	s_nop 0
	v_cndmask_b32_e32 v0, v0, v70, vcc
	v_sqrt_f32_e32 v70, v0
	s_nop 0
	v_add_u32_e32 v71, -1, v70
	v_fma_f32 v72, -v71, v70, v0
	v_cmp_ge_f32_e64 s[6:7], 0, v72
	v_add_u32_e32 v72, 1, v70
	s_nop 0
	v_cndmask_b32_e64 v71, v70, v71, s[6:7]
	v_fma_f32 v70, -v72, v70, v0
	v_cmp_lt_f32_e64 s[6:7], 0, v70
	s_nop 1
	v_cndmask_b32_e64 v70, v71, v72, s[6:7]
	v_mul_f32_e32 v71, 0x37800000, v70
	v_cndmask_b32_e32 v70, v70, v71, vcc
	v_cmp_class_f32_e32 vcc, v0, v221
	s_nop 1
	v_cndmask_b32_e32 v0, v70, v0, vcc
	v_div_scale_f32 v70, s[6:7], v0, v0, 1.0
	v_rcp_f32_e32 v71, v70
	s_nop 0
	v_fma_f32 v72, -v70, v71, 1.0
	v_fmac_f32_e32 v71, v72, v71
	v_div_scale_f32 v72, vcc, 1.0, v0, 1.0
	v_mul_f32_e32 v73, v72, v71
	v_fma_f32 v74, -v70, v73, v72
	v_fmac_f32_e32 v73, v74, v71
	v_fma_f32 v70, -v70, v73, v72
	v_div_fmas_f32 v70, v70, v71, v73
	v_div_fixup_f32 v0, v70, v0, 1.0
	v_pk_mul_f32 v[66:67], v[66:67], v[0:1] op_sel_hi:[1,0]
	v_pk_mul_f32 v[68:69], v[68:69], v[0:1] op_sel_hi:[1,0]
	v_pk_mul_f32 v[62:63], v[62:63], v[0:1] op_sel_hi:[1,0]
	v_pk_mul_f32 v[64:65], v[64:65], v[0:1] op_sel_hi:[1,0]
	v_mad_i64_i32 v[70:71], s[6:7], v173, s44, v[160:161]
	v_pk_mul_f32 v[68:69], v[148:149], v[68:69]
	v_pk_mul_f32 v[66:67], v[150:151], v[66:67]
	v_pk_mul_f32 v[72:73], v[144:145], v[64:65]
	v_pk_mul_f32 v[64:65], v[146:147], v[62:63]
	v_lshl_add_u64 v[70:71], v[70:71], 0, v[162:163]
	v_cvt_pk_bf16_f32 v62, v66, v67
	v_cvt_pk_bf16_f32 v63, v68, v69
	v_cvt_pk_bf16_f32 v64, v64, v65
	v_cvt_pk_bf16_f32 v65, v72, v73
	v_pk_mul_f32 v[58:59], v[58:59], v[0:1] op_sel_hi:[1,0]
	v_pk_mul_f32 v[60:61], v[60:61], v[0:1] op_sel_hi:[1,0]
	v_pk_mul_f32 v[54:55], v[54:55], v[0:1] op_sel_hi:[1,0]
	v_pk_mul_f32 v[56:57], v[56:57], v[0:1] op_sel_hi:[1,0]
	global_store_dwordx4 v[70:71], v[62:65], off nt
	v_pk_mul_f32 v[60:61], v[156:157], v[60:61]
	v_pk_mul_f32 v[58:59], v[158:159], v[58:59]
	v_pk_mul_f32 v[62:63], v[152:153], v[56:57]
	v_pk_mul_f32 v[56:57], v[154:155], v[54:55]
	v_cvt_pk_bf16_f32 v54, v58, v59
	v_cvt_pk_bf16_f32 v55, v60, v61
	v_cvt_pk_bf16_f32 v56, v56, v57
	v_cvt_pk_bf16_f32 v57, v62, v63
	global_store_dwordx4 v[70:71], v[54:57], off offset:64 nt
	v_mul_f32_e32 v0, v38, v38
	s_nop 0
	v_pk_mul_f32 v[54:55], v[52:53], v[52:53]
	v_pk_mul_f32 v[56:57], v[50:51], v[50:51]
	s_nop 0
	v_pk_mov_b32 v[58:59], v[56:57], v[54:55] op_sel:[1,0]
	v_mov_b32_e32 v57, v55
	v_pk_add_f32 v[54:55], v[58:59], v[56:57]
	v_pk_mul_f32 v[56:57], v[48:49], v[48:49]
	v_pk_mul_f32 v[58:59], v[46:47], v[46:47]
	v_pk_add_f32 v[54:55], v[54:55], v[54:55] op_sel:[0,1] op_sel_hi:[1,0]
	v_pk_mov_b32 v[60:61], v[58:59], v[56:57] op_sel:[1,0]
	v_mov_b32_e32 v59, v57
	v_pk_add_f32 v[56:57], v[60:61], v[58:59]
	v_mul_f32_e32 v58, v39, v39
	v_pk_add_f32 v[56:57], v[56:57], v[56:57] op_sel:[0,1] op_sel_hi:[1,0]
	v_mov_b32_e32 v55, v0
	v_mov_b32_e32 v57, v58
	v_mul_f32_e32 v0, v43, v43
	v_mul_f32_e32 v59, v40, v40
	v_pk_add_f32 v[54:55], v[54:55], v[56:57]
	v_pk_fma_f32 v[56:57], v[42:43], v[42:43], v[0:1] op_sel_hi:[1,1,0]
	v_mul_f32_e32 v0, v45, v45
	v_mul_f32_e32 v60, v41, v41
	v_mov_b32_e32 v57, v59
	v_pk_fma_f32 v[58:59], v[44:45], v[44:45], v[0:1] op_sel_hi:[1,1,0]
	s_nop 0
	v_mov_b32_e32 v59, v60
	v_pk_add_f32 v[56:57], v[56:57], v[58:59]
	s_nop 0
	v_pk_add_f32 v[54:55], v[54:55], v[56:57]
	s_nop 0
	v_add_f32_e32 v0, v54, v55
	s_waitcnt lgkmcnt(0)
	v_mov_b32_e32 v54, v0
	v_mov_b32_e32 v253, v0
	s_nop 1
	v_permlane16_swap_b32_e32 v54, v253
	v_add_f32_e32 v0, v54, v253
	s_waitcnt lgkmcnt(0)
	v_mov_b32_e32 v54, v0
	v_mov_b32_e32 v253, v0
	s_nop 1
	v_permlane32_swap_b32_e32 v54, v253
	v_add_f32_e32 v0, v54, v253
	v_fmamk_f32 v0, v0, 0x3c800000, v220
	v_cmp_gt_f32_e32 vcc, s45, v0
	v_mul_f32_e32 v54, 0x4f800000, v0
	s_nop 0
	v_cndmask_b32_e32 v0, v0, v54, vcc
	v_sqrt_f32_e32 v54, v0
	s_nop 0
	v_add_u32_e32 v55, -1, v54
	v_fma_f32 v56, -v55, v54, v0
	v_cmp_ge_f32_e64 s[6:7], 0, v56
	v_add_u32_e32 v56, 1, v54
	s_nop 0
	v_cndmask_b32_e64 v55, v54, v55, s[6:7]
	v_fma_f32 v54, -v56, v54, v0
	v_cmp_lt_f32_e64 s[6:7], 0, v54
	s_nop 1
	v_cndmask_b32_e64 v54, v55, v56, s[6:7]
	v_mul_f32_e32 v55, 0x37800000, v54
	v_cndmask_b32_e32 v54, v54, v55, vcc
	v_cmp_class_f32_e32 vcc, v0, v221
	s_nop 1
	v_cndmask_b32_e32 v0, v54, v0, vcc
	v_div_scale_f32 v54, s[6:7], v0, v0, 1.0
	v_rcp_f32_e32 v55, v54
	s_nop 0
	v_fma_f32 v56, -v54, v55, 1.0
	v_fmac_f32_e32 v55, v56, v55
	v_div_scale_f32 v56, vcc, 1.0, v0, 1.0
	v_mul_f32_e32 v57, v56, v55
	v_fma_f32 v58, -v54, v57, v56
	v_fmac_f32_e32 v57, v58, v55
	v_fma_f32 v54, -v54, v57, v56
	v_div_fmas_f32 v54, v54, v55, v57
	v_div_fixup_f32 v0, v54, v0, 1.0
	v_pk_mul_f32 v[50:51], v[50:51], v[0:1] op_sel_hi:[1,0]
	v_pk_mul_f32 v[52:53], v[52:53], v[0:1] op_sel_hi:[1,0]
	v_pk_mul_f32 v[46:47], v[46:47], v[0:1] op_sel_hi:[1,0]
	v_pk_mul_f32 v[48:49], v[48:49], v[0:1] op_sel_hi:[1,0]
	v_mad_i64_i32 v[54:55], s[6:7], v172, s44, v[160:161]
	v_pk_mul_f32 v[52:53], v[148:149], v[52:53]
	v_pk_mul_f32 v[50:51], v[150:151], v[50:51]
	v_pk_mul_f32 v[56:57], v[144:145], v[48:49]
	v_pk_mul_f32 v[48:49], v[146:147], v[46:47]
	v_lshl_add_u64 v[54:55], v[54:55], 0, v[162:163]
	v_cvt_pk_bf16_f32 v46, v50, v51
	v_cvt_pk_bf16_f32 v47, v52, v53
	v_cvt_pk_bf16_f32 v48, v48, v49
	v_cvt_pk_bf16_f32 v49, v56, v57
; #define PG8_GAS __attribute__((address_space(1)))
; __device__ __forceinline__ unsigned cvtpk(float lo, float hi) { f32x2 v = {lo, hi}; bf16x2_t b = __builtin_convertvector(v, bf16x2_t); return __builtin_bit_cast(unsigned, b); }
;     __device__ __forceinline__ void operator()(const f32x4 (&acc)[2][2][4][2], const Unit& u, int wr, int wc, int fr, int fq) const {
;     ...
;                     float ss = 0.f;
; #pragma unroll
;                     for (int bj = 0; bj < 2; ++bj)
; #pragma unroll
;                         for (int n = 0; n < 2; ++n) { const f32x4 x = acc[ai][bj][m][n]; ss += (x[0] * x[0] + x[1] * x[1]) + (x[2] * x[2] + x[3] * x[3]); }
;                     ss += __shfl_xor(ss, 16); ss += __shfl_xor(ss, 32);
;                     const float rstd = 1.0f / sqrtf(ss * (1.0f / 64.0f) + 1e-6f);
;                     bf16_t* p = O + (size_t)(row0 + ai * HALF + m * 16) * 3072 + colh;
; #pragma unroll
;                     for (int bj = 0; bj < 2; ++bj) {
;                         const f32x4 v0 = acc[ai][bj][m][0] * rstd * gv[bj][0], v1 = acc[ai][bj][m][1] * rstd * gv[bj][1];
;                         u32x4 w; w.x = cvtpk(v0[0], v0[1]); w.y = cvtpk(v0[2], v0[3]); w.z = cvtpk(v1[0], v1[1]); w.w = cvtpk(v1[2], v1[3]);
;                         __builtin_nontemporal_store(w, (PG8_GAS u32x4*)(p + 32 * bj));
;                     }
	v_pk_mul_f32 v[42:43], v[42:43], v[0:1] op_sel_hi:[1,0]
	v_pk_mul_f32 v[44:45], v[44:45], v[0:1] op_sel_hi:[1,0]
	v_pk_mul_f32 v[38:39], v[38:39], v[0:1] op_sel_hi:[1,0]
	v_pk_mul_f32 v[40:41], v[40:41], v[0:1] op_sel_hi:[1,0]
	global_store_dwordx4 v[54:55], v[46:49], off nt
	v_pk_mul_f32 v[44:45], v[156:157], v[44:45]
	v_pk_mul_f32 v[42:43], v[158:159], v[42:43]
	v_pk_mul_f32 v[46:47], v[152:153], v[40:41]
	v_pk_mul_f32 v[40:41], v[154:155], v[38:39]
	v_cvt_pk_bf16_f32 v38, v42, v43
	v_cvt_pk_bf16_f32 v39, v44, v45
	v_cvt_pk_bf16_f32 v40, v40, v41
	v_cvt_pk_bf16_f32 v41, v46, v47
	global_store_dwordx4 v[54:55], v[38:41], off offset:64 nt
	v_mul_f32_e32 v0, v22, v22
	s_nop 0
	v_pk_mul_f32 v[38:39], v[36:37], v[36:37]
	v_pk_mul_f32 v[40:41], v[34:35], v[34:35]
	s_nop 0
	v_pk_mov_b32 v[42:43], v[40:41], v[38:39] op_sel:[1,0]
	v_mov_b32_e32 v41, v39
	v_pk_add_f32 v[38:39], v[42:43], v[40:41]
	v_pk_mul_f32 v[40:41], v[32:33], v[32:33]
	v_pk_mul_f32 v[42:43], v[30:31], v[30:31]
	v_pk_add_f32 v[38:39], v[38:39], v[38:39] op_sel:[0,1] op_sel_hi:[1,0]
	v_pk_mov_b32 v[44:45], v[42:43], v[40:41] op_sel:[1,0]
	v_mov_b32_e32 v43, v41
	v_pk_add_f32 v[40:41], v[44:45], v[42:43]
	v_mul_f32_e32 v42, v23, v23
	v_pk_add_f32 v[40:41], v[40:41], v[40:41] op_sel:[0,1] op_sel_hi:[1,0]
	v_mov_b32_e32 v39, v0
	v_mov_b32_e32 v41, v42
	v_mul_f32_e32 v0, v27, v27
	v_mul_f32_e32 v43, v24, v24
	v_pk_add_f32 v[38:39], v[38:39], v[40:41]
	v_pk_fma_f32 v[40:41], v[26:27], v[26:27], v[0:1] op_sel_hi:[1,1,0]
	v_mul_f32_e32 v0, v29, v29
	v_mul_f32_e32 v44, v25, v25
	v_mov_b32_e32 v41, v43
	v_pk_fma_f32 v[42:43], v[28:29], v[28:29], v[0:1] op_sel_hi:[1,1,0]
	s_nop 0
	v_mov_b32_e32 v43, v44
	v_pk_add_f32 v[40:41], v[40:41], v[42:43]
	s_nop 0
	v_pk_add_f32 v[38:39], v[38:39], v[40:41]
	s_nop 0
	v_add_f32_e32 v0, v38, v39
	s_waitcnt lgkmcnt(0)
	v_mov_b32_e32 v38, v0
	v_mov_b32_e32 v253, v0
	s_nop 1
	v_permlane16_swap_b32_e32 v38, v253
	v_add_f32_e32 v0, v38, v253
	s_waitcnt lgkmcnt(0)
	v_mov_b32_e32 v38, v0
	v_mov_b32_e32 v253, v0
	s_nop 1
	v_permlane32_swap_b32_e32 v38, v253
	v_add_f32_e32 v0, v38, v253
	v_fmamk_f32 v0, v0, 0x3c800000, v220
	v_cmp_gt_f32_e32 vcc, s45, v0
	v_mul_f32_e32 v38, 0x4f800000, v0
	s_nop 0
	v_cndmask_b32_e32 v0, v0, v38, vcc
	v_sqrt_f32_e32 v38, v0
	s_nop 0
	v_add_u32_e32 v39, -1, v38
	v_fma_f32 v40, -v39, v38, v0
	v_cmp_ge_f32_e64 s[6:7], 0, v40
	v_add_u32_e32 v40, 1, v38
	s_nop 0
	v_cndmask_b32_e64 v39, v38, v39, s[6:7]
	v_fma_f32 v38, -v40, v38, v0
	v_cmp_lt_f32_e64 s[6:7], 0, v38
	s_nop 1
	v_cndmask_b32_e64 v38, v39, v40, s[6:7]
	v_mul_f32_e32 v39, 0x37800000, v38
	v_cndmask_b32_e32 v38, v38, v39, vcc
	v_cmp_class_f32_e32 vcc, v0, v221
	s_nop 1
	v_cndmask_b32_e32 v0, v38, v0, vcc
	v_div_scale_f32 v38, s[6:7], v0, v0, 1.0
	v_rcp_f32_e32 v39, v38
	s_nop 0
	v_fma_f32 v40, -v38, v39, 1.0
	v_fmac_f32_e32 v39, v40, v39
	v_div_scale_f32 v40, vcc, 1.0, v0, 1.0
	v_mul_f32_e32 v41, v40, v39
	v_fma_f32 v42, -v38, v41, v40
	v_fmac_f32_e32 v41, v42, v39
	v_fma_f32 v38, -v38, v41, v40
	v_div_fmas_f32 v38, v38, v39, v41
	v_div_fixup_f32 v0, v38, v0, 1.0
	v_pk_mul_f32 v[34:35], v[34:35], v[0:1] op_sel_hi:[1,0]
	v_pk_mul_f32 v[36:37], v[36:37], v[0:1] op_sel_hi:[1,0]
	v_pk_mul_f32 v[30:31], v[30:31], v[0:1] op_sel_hi:[1,0]
	v_pk_mul_f32 v[32:33], v[32:33], v[0:1] op_sel_hi:[1,0]
	v_mad_i64_i32 v[38:39], s[6:7], v169, s44, v[160:161]
	v_pk_mul_f32 v[36:37], v[148:149], v[36:37]
	v_pk_mul_f32 v[34:35], v[150:151], v[34:35]
	v_pk_mul_f32 v[40:41], v[144:145], v[32:33]
	v_pk_mul_f32 v[32:33], v[146:147], v[30:31]
	v_lshl_add_u64 v[38:39], v[38:39], 0, v[162:163]
	v_cvt_pk_bf16_f32 v30, v34, v35
	v_cvt_pk_bf16_f32 v31, v36, v37
	v_cvt_pk_bf16_f32 v32, v32, v33
	v_cvt_pk_bf16_f32 v33, v40, v41
	v_pk_mul_f32 v[26:27], v[26:27], v[0:1] op_sel_hi:[1,0]
	v_pk_mul_f32 v[28:29], v[28:29], v[0:1] op_sel_hi:[1,0]
	v_pk_mul_f32 v[22:23], v[22:23], v[0:1] op_sel_hi:[1,0]
	v_pk_mul_f32 v[24:25], v[24:25], v[0:1] op_sel_hi:[1,0]
	global_store_dwordx4 v[38:39], v[30:33], off nt
	v_pk_mul_f32 v[28:29], v[156:157], v[28:29]
	v_pk_mul_f32 v[26:27], v[158:159], v[26:27]
	v_pk_mul_f32 v[30:31], v[152:153], v[24:25]
	v_pk_mul_f32 v[24:25], v[154:155], v[22:23]
	v_cvt_pk_bf16_f32 v22, v26, v27
	v_cvt_pk_bf16_f32 v23, v28, v29
	v_cvt_pk_bf16_f32 v24, v24, v25
	v_cvt_pk_bf16_f32 v25, v30, v31
	global_store_dwordx4 v[38:39], v[22:25], off offset:64 nt
	v_mul_f32_e32 v0, v6, v6
	s_nop 0
	v_pk_mul_f32 v[22:23], v[20:21], v[20:21]
	v_pk_mul_f32 v[24:25], v[18:19], v[18:19]
	s_nop 0
	v_pk_mov_b32 v[26:27], v[24:25], v[22:23] op_sel:[1,0]
	v_mov_b32_e32 v25, v23
	v_pk_add_f32 v[22:23], v[26:27], v[24:25]
	v_pk_mul_f32 v[24:25], v[16:17], v[16:17]
	v_pk_mul_f32 v[26:27], v[14:15], v[14:15]
	v_pk_add_f32 v[22:23], v[22:23], v[22:23] op_sel:[0,1] op_sel_hi:[1,0]
	v_pk_mov_b32 v[28:29], v[26:27], v[24:25] op_sel:[1,0]
	v_mov_b32_e32 v27, v25
	v_pk_add_f32 v[24:25], v[28:29], v[26:27]
	v_mul_f32_e32 v26, v7, v7
	v_pk_add_f32 v[24:25], v[24:25], v[24:25] op_sel:[0,1] op_sel_hi:[1,0]
	v_mov_b32_e32 v23, v0
	v_mov_b32_e32 v25, v26
	v_mul_f32_e32 v0, v11, v11
	v_mul_f32_e32 v27, v8, v8
	v_pk_add_f32 v[22:23], v[22:23], v[24:25]
	v_pk_fma_f32 v[24:25], v[10:11], v[10:11], v[0:1] op_sel_hi:[1,1,0]
	v_mul_f32_e32 v0, v13, v13
	v_mul_f32_e32 v28, v9, v9
	v_mov_b32_e32 v25, v27
	v_pk_fma_f32 v[26:27], v[12:13], v[12:13], v[0:1] op_sel_hi:[1,1,0]
	s_nop 0
	v_mov_b32_e32 v27, v28
	v_pk_add_f32 v[24:25], v[24:25], v[26:27]
	s_nop 0
	v_pk_add_f32 v[22:23], v[22:23], v[24:25]
	s_nop 0
	v_add_f32_e32 v0, v22, v23
	s_waitcnt lgkmcnt(0)
; #define PG8_GAS __attribute__((address_space(1)))
; __device__ __forceinline__ unsigned cvtpk(float lo, float hi) { f32x2 v = {lo, hi}; bf16x2_t b = __builtin_convertvector(v, bf16x2_t); return __builtin_bit_cast(unsigned, b); }
;     __device__ __forceinline__ void operator()(const f32x4 (&acc)[2][2][4][2], const Unit& u, int wr, int wc, int fr, int fq) const {
;     ...
;                     ss += __shfl_xor(ss, 16); ss += __shfl_xor(ss, 32);
;                     const float rstd = 1.0f / sqrtf(ss * (1.0f / 64.0f) + 1e-6f);
;                     bf16_t* p = O + (size_t)(row0 + ai * HALF + m * 16) * 3072 + colh;
; #pragma unroll
;                     for (int bj = 0; bj < 2; ++bj) {
;                         const f32x4 v0 = acc[ai][bj][m][0] * rstd * gv[bj][0], v1 = acc[ai][bj][m][1] * rstd * gv[bj][1];
;                         u32x4 w; w.x = cvtpk(v0[0], v0[1]); w.y = cvtpk(v0[2], v0[3]); w.z = cvtpk(v1[0], v1[1]); w.w = cvtpk(v1[2], v1[3]);
;                         __builtin_nontemporal_store(w, (PG8_GAS u32x4*)(p + 32 * bj));
;                     }
	v_mov_b32_e32 v22, v0
	v_mov_b32_e32 v253, v0
	s_nop 1
	v_permlane16_swap_b32_e32 v22, v253
	v_add_f32_e32 v0, v22, v253
	s_waitcnt lgkmcnt(0)
	v_mov_b32_e32 v22, v0
	v_mov_b32_e32 v253, v0
	s_nop 1
	v_permlane32_swap_b32_e32 v22, v253
	v_add_f32_e32 v0, v22, v253
	v_fmamk_f32 v0, v0, 0x3c800000, v220
	v_cmp_gt_f32_e32 vcc, s45, v0
	v_mul_f32_e32 v22, 0x4f800000, v0
	s_nop 0
	v_cndmask_b32_e32 v0, v0, v22, vcc
	v_sqrt_f32_e32 v22, v0
	s_nop 0
	v_add_u32_e32 v23, -1, v22
	v_fma_f32 v24, -v23, v22, v0
	v_cmp_ge_f32_e64 s[6:7], 0, v24
	v_add_u32_e32 v24, 1, v22
	s_nop 0
	v_cndmask_b32_e64 v23, v22, v23, s[6:7]
	v_fma_f32 v22, -v24, v22, v0
	v_cmp_lt_f32_e64 s[6:7], 0, v22
	s_nop 1
	v_cndmask_b32_e64 v22, v23, v24, s[6:7]
	v_mul_f32_e32 v23, 0x37800000, v22
	v_cndmask_b32_e32 v22, v22, v23, vcc
	v_cmp_class_f32_e32 vcc, v0, v221
	s_nop 1
	v_cndmask_b32_e32 v0, v22, v0, vcc
	v_div_scale_f32 v22, s[6:7], v0, v0, 1.0
	v_rcp_f32_e32 v23, v22
	s_nop 0
	v_fma_f32 v24, -v22, v23, 1.0
	v_fmac_f32_e32 v23, v24, v23
	v_div_scale_f32 v24, vcc, 1.0, v0, 1.0
	v_mul_f32_e32 v25, v24, v23
	v_fma_f32 v26, -v22, v25, v24
	v_fmac_f32_e32 v25, v26, v23
	v_fma_f32 v22, -v22, v25, v24
	v_div_fmas_f32 v22, v22, v23, v25
	v_div_fixup_f32 v0, v22, v0, 1.0
	v_mad_i64_i32 v[22:23], s[6:7], v168, s44, v[160:161]
	v_pk_mul_f32 v[18:19], v[18:19], v[0:1] op_sel_hi:[1,0]
	v_pk_mul_f32 v[20:21], v[20:21], v[0:1] op_sel_hi:[1,0]
	v_pk_mul_f32 v[14:15], v[14:15], v[0:1] op_sel_hi:[1,0]
	v_pk_mul_f32 v[16:17], v[16:17], v[0:1] op_sel_hi:[1,0]
	v_lshl_add_u64 v[160:161], v[22:23], 0, v[162:163]
	v_pk_mul_f32 v[20:21], v[148:149], v[20:21]
	v_pk_mul_f32 v[18:19], v[150:151], v[18:19]
	v_pk_mul_f32 v[22:23], v[144:145], v[16:17]
	v_pk_mul_f32 v[16:17], v[146:147], v[14:15]
	v_pk_mul_f32 v[10:11], v[10:11], v[0:1] op_sel_hi:[1,0]
	v_pk_mul_f32 v[12:13], v[12:13], v[0:1] op_sel_hi:[1,0]
	v_pk_mul_f32 v[6:7], v[6:7], v[0:1] op_sel_hi:[1,0]
	v_pk_mul_f32 v[8:9], v[8:9], v[0:1] op_sel_hi:[1,0]
	v_cvt_pk_bf16_f32 v14, v18, v19
	v_cvt_pk_bf16_f32 v15, v20, v21
	v_cvt_pk_bf16_f32 v16, v16, v17
	v_cvt_pk_bf16_f32 v17, v22, v23
	v_pk_mul_f32 v[12:13], v[156:157], v[12:13]
	v_pk_mul_f32 v[10:11], v[158:159], v[10:11]
	v_pk_mul_f32 v[8:9], v[152:153], v[8:9]
	v_pk_mul_f32 v[6:7], v[154:155], v[6:7]
	global_store_dwordx4 v[160:161], v[14:17], off nt
